# v013 plus one static s_setprio 3 for waves 0-3 over each attention kv loop
# speedup vs baseline: 1.0069x; 1.0016x over previous
.Lh1_first:
	s_cmp_gt_u32 s96, 3
	s_cbranch_scc1 .Lprio_skip
	s_setprio 3
